# speedup vs baseline: 1.0083x; 1.0083x over previous
; #define A64_GLOAD(t) do { A64_IDX(); const char* Kt = (const char*)(Kg + (size_t)(t) * 64 * ldk); const char* Vt = (const char*)(Vg + (size_t)(t) * 64 * ldv); \
;         kreg0 = *(const u32x4*)(Kt + (unsigned)(kk0 * ldk + kc0 * 8) * 2u); if (k2) kreg1 = *(const u32x4*)(Kt + (unsigned)(kk1 * ldk + kc1 * 8) * 2u); vreg = *(const u32x4*)(Vt + (unsigned)(vk * ldv + vc * 8) * 2u); } while (0)
; #define A64_LWRITE(bo) do { A64_IDX(); *(LAS u32x4*)(lds + (bo) + kk0 * KP + kc0 * 16) = kreg0; if (k2) *(LAS u32x4*)(lds + (bo) + kk1 * KP + kc1 * 16) = kreg1; \
;         *(LAS u32x4*)(lds + (bo) + KBYTES + (vc >> 2) * 4096 + vk * 64 + (vc & 3) * 16) = vreg; } while (0)
; #define A64_KREAD(bo, half) do { _Pragma("unroll") for (int ds = 0; ds < NDS; ++ds) kf[ds] = *(const LAS bf16x8*)(lds + (bo) + kfr + (half) * 32 * KP + ds * 32); } while (0)
; #define A64_S(dst, q) do { _Pragma("unroll") for (int i = 0; i < 16; ++i) dst[i] = 0.f; _Pragma("unroll") for (int ds = 0; ds < NDS; ++ds) dst = __builtin_amdgcn_mfma_f32_32x32x16_bf16(kf[ds], q[ds], dst, 0, 0, 0); } while (0)
; #define A64_EXP(s, l0, l1, p) do { _Pragma("unroll") for (int i = 0; i < 16; i += 2) { s[i] = __builtin_amdgcn_exp2f(s[i]); s[i + 1] = __builtin_amdgcn_exp2f(s[i + 1]); l0 += s[i]; l1 += s[i + 1]; } \
;         p[0] = pack8(s, 0); p[1] = pack8(s, 1); } while (0)
; #define A64_SB() __builtin_amdgcn_sched_barrier(0)
; template <int DQK>
; __device__ __forceinline__ void attn_unit64p(LAS char* lds, const bf16x8 (&qa)[DQK / 16], const bf16x8 (&qb)[DQK / 16],
;                                              const bf16_t* Kg, int ldk, const bf16_t* Vg, int ldv, int nt, bf16_t* Obase, int ldo, int ogb_off) {
;     ...
;     A64_GLOAD(0); A64_LWRITE(0);
;     __syncthreads();
;     if (nt > 1) A64_GLOAD(1);
;     A64_KREAD(0, 0);
; #pragma nounroll
;     for (int j = 0; j < 2 * nt; ++j) {
;         const int t = j >> 1, hf = j & 1;
;         const unsigned bo = (t & 1) * BUF, bn = ((t & 1) ^ 1) * BUF;
;         const unsigned vo = bo + hf * 2048;
;         const unsigned ko = hf ? bn : bo + 32 * KP;
;         A64_SB(); A64_S(sa, qa); A64_EXP(sb, lb0, lb1, pb);
;         A64_SB(); A64_PV(ob0, ob1, pb);
;         A64_SB(); A64_S(sb, qb); A64_EXP(sa, la0, la1, pa); A64_VREAD(vo, 0);
;         A64_SB(); A64_KREAD(ko, 0); A64_PV(oa0, oa1, pa);
.Lp11_g1_pro:
	s_mov_b32 s24, 0x2000
	s_mov_b32 s25, 0
	v_lshl_add_u64 v[180:181], v[168:169], 0, s[24:25]
	global_load_dwordx4 v[104:107], v[180:181], off
	v_mov_b32_e32 v64, 0xf149f2ca
	v_mov_b32_e32 v65, v64
	v_mov_b32_e32 v66, v64
	v_mov_b32_e32 v67, v64
	v_mov_b32_e32 v68, v64
	v_mov_b32_e32 v69, v64
	v_mov_b32_e32 v70, v64
	v_mov_b32_e32 v71, v64
	v_mov_b32_e32 v72, v64
	v_mov_b32_e32 v73, v64
	v_mov_b32_e32 v74, v64
	v_mov_b32_e32 v75, v64
	v_mov_b32_e32 v76, v64
	v_mov_b32_e32 v77, v64
	v_mov_b32_e32 v78, v64
	v_mov_b32_e32 v79, v64
	v_mov_b32_e32 v214, 0
	v_mov_b32_e32 v215, 0
	v_mov_b32_e32 v216, 0
	v_mov_b32_e32 v217, 0
	v_mov_b32_e32 v218, 0
	v_mov_b32_e32 v219, 0
	v_mov_b32_e32 v220, 0
	v_mov_b32_e32 v221, 0
	v_mov_b32_e32 v248, 0
	v_mov_b32_e32 v249, 0
	v_mov_b32_e32 v250, 0
	v_mov_b32_e32 v251, 0
	v_mov_b32_e32 v252, 0
	v_mov_b32_e32 v253, 0
	v_mov_b32_e32 v254, 0
	v_mov_b32_e32 v255, 0
	s_cmp_eq_u64 s[0:1], 0
	s_cbranch_scc1 .Lp11_noprio
	s_setprio 1
.Lp11_noprio:
.Lp11_loop:
	s_waitcnt lgkmcnt(0)
	v_mfma_f32_32x32x16_bf16 v[80:95], v[182:185], v[128:131], 0
	v_exp_f32_e32 v64, v64
	v_exp_f32_e32 v65, v65
	v_exp_f32_e32 v66, v66
	v_exp_f32_e32 v67, v67
	v_mfma_f32_32x32x16_bf16 v[80:95], v[186:189], v[124:127], v[80:95]
	v_exp_f32_e32 v68, v68
	v_exp_f32_e32 v69, v69
	v_cvt_pk_bf16_f32 v230, v64, v65
	v_cvt_pk_bf16_f32 v231, v66, v67
	v_mfma_f32_32x32x16_bf16 v[80:95], v[190:193], v[120:123], v[80:95]
	v_exp_f32_e32 v70, v70
	v_exp_f32_e32 v71, v71
	v_exp_f32_e32 v72, v72
	v_cvt_pk_bf16_f32 v232, v68, v69
	v_mfma_f32_32x32x16_bf16 v[80:95], v[194:197], v[116:119], v[80:95]
	v_exp_f32_e32 v73, v73
	v_exp_f32_e32 v74, v74
	v_cvt_pk_bf16_f32 v233, v70, v71
	v_exp_f32_e32 v75, v75
	v_mfma_f32_32x32x16_bf16 v[80:95], v[198:201], v[108:111], v[80:95]
	v_exp_f32_e32 v76, v76
	v_exp_f32_e32 v77, v77
	v_cvt_pk_bf16_f32 v234, v72, v73
	v_cvt_pk_bf16_f32 v235, v74, v75
	v_mfma_f32_32x32x16_bf16 v[80:95], v[202:205], v[112:115], v[80:95]
	v_exp_f32_e32 v78, v78
	v_exp_f32_e32 v79, v79
	v_cvt_pk_bf16_f32 v236, v76, v77
	v_cvt_pk_bf16_f32 v237, v78, v79
	v_mfma_f32_32x32x16_bf16 v[16:31], v[248:251], v[230:233], v[16:31]
	ds_read_b64_tr_b16 v[248:249], v239 offset:13312
	ds_read_b64_tr_b16 v[250:251], v239 offset:13824
	v_add_f32_e32 v172, v172, v64
	v_add_f32_e32 v173, v173, v65
	v_add_f32_e32 v172, v172, v66
	v_add_f32_e32 v173, v173, v67
	v_mfma_f32_32x32x16_bf16 v[0:15], v[252:255], v[230:233], v[0:15]
	ds_read_b64_tr_b16 v[252:253], v239 offset:17408
	ds_read_b64_tr_b16 v[254:255], v239 offset:17920
	v_add_f32_e32 v172, v172, v68
	v_add_f32_e32 v173, v173, v69
	v_add_f32_e32 v172, v172, v70
	v_add_f32_e32 v173, v173, v71
	v_mfma_f32_32x32x16_bf16 v[16:31], v[214:217], v[234:237], v[16:31]
	ds_read_b64_tr_b16 v[214:215], v239 offset:14336
	ds_read_b64_tr_b16 v[216:217], v239 offset:14848
	v_add_f32_e32 v172, v172, v72
	v_add_f32_e32 v173, v173, v73
	v_add_f32_e32 v172, v172, v74
	v_add_f32_e32 v173, v173, v75
	v_mfma_f32_32x32x16_bf16 v[0:15], v[218:221], v[234:237], v[0:15]
	ds_read_b64_tr_b16 v[218:219], v239 offset:18432
	ds_read_b64_tr_b16 v[220:221], v239 offset:18944
	v_add_f32_e32 v172, v172, v76
	v_add_f32_e32 v173, v173, v77
	v_add_f32_e32 v172, v172, v78
	v_add_f32_e32 v173, v173, v79
	v_mfma_f32_32x32x16_bf16 v[64:79], v[182:185], v[132:135], 0
	ds_read_b128 v[182:185], v238 offset:6656
	v_exp_f32_e32 v80, v80
	v_exp_f32_e32 v81, v81
	v_exp_f32_e32 v82, v82
	v_exp_f32_e32 v83, v83
	v_mfma_f32_32x32x16_bf16 v[64:79], v[186:189], v[136:139], v[64:79]
	ds_read_b128 v[186:189], v238 offset:6688
	v_exp_f32_e32 v84, v84
	v_exp_f32_e32 v85, v85
	v_cvt_pk_bf16_f32 v222, v80, v81
	v_cvt_pk_bf16_f32 v223, v82, v83
	v_mfma_f32_32x32x16_bf16 v[64:79], v[190:193], v[140:143], v[64:79]
	ds_read_b128 v[190:193], v238 offset:6720
	v_exp_f32_e32 v86, v86
	v_exp_f32_e32 v87, v87
	v_exp_f32_e32 v88, v88
	v_cvt_pk_bf16_f32 v224, v84, v85
	v_mfma_f32_32x32x16_bf16 v[64:79], v[194:197], v[144:147], v[64:79]
	ds_read_b128 v[194:197], v238 offset:6752
	v_exp_f32_e32 v89, v89
	v_exp_f32_e32 v90, v90
	v_cvt_pk_bf16_f32 v225, v86, v87
	v_exp_f32_e32 v91, v91
	v_mfma_f32_32x32x16_bf16 v[64:79], v[198:201], v[148:151], v[64:79]
	ds_read_b128 v[198:201], v238 offset:6784
	v_exp_f32_e32 v92, v92
	v_exp_f32_e32 v93, v93
	v_cvt_pk_bf16_f32 v226, v88, v89
	v_cvt_pk_bf16_f32 v227, v90, v91
	v_mfma_f32_32x32x16_bf16 v[64:79], v[202:205], v[152:155], v[64:79]
	ds_read_b128 v[202:205], v238 offset:6816
	v_exp_f32_e32 v94, v94
	v_exp_f32_e32 v95, v95
	v_cvt_pk_bf16_f32 v228, v92, v93
	v_cvt_pk_bf16_f32 v229, v94, v95
	s_waitcnt lgkmcnt(6)
	v_mfma_f32_32x32x16_bf16 v[32:47], v[248:251], v[222:225], v[32:47]
	v_add_f32_e32 v170, v170, v80
	v_add_f32_e32 v171, v171, v81
	v_add_f32_e32 v170, v170, v82
	v_add_f32_e32 v171, v171, v83
	s_waitcnt vmcnt(0)
	ds_write_b128 v159, v[96:99] offset:21504
	s_cmp_eq_u64 s[0:1], 0
	v_mfma_f32_32x32x16_bf16 v[48:63], v[252:255], v[222:225], v[48:63]
	v_add_f32_e32 v170, v170, v84
	v_add_f32_e32 v171, v171, v85
	v_add_f32_e32 v170, v170, v86
	v_add_f32_e32 v171, v171, v87
	s_cbranch_scc1 .Lp11_w1_a0
	ds_write_b128 v212, v[100:103] offset:21504

; #define A64_EXP(s, l0, l1, p) do { _Pragma("unroll") for (int i = 0; i < 16; i += 2) { s[i] = __builtin_amdgcn_exp2f(s[i]); s[i + 1] = __builtin_amdgcn_exp2f(s[i + 1]); l0 += s[i]; l1 += s[i + 1]; } \
;         p[0] = pack8(s, 0); p[1] = pack8(s, 1); } while (0)
; #define A64_PV(o0, o1, p) do { o0 = __builtin_amdgcn_mfma_f32_32x32x16_bf16(vf[0], p[0], o0, 0, 0, 0); o1 = __builtin_amdgcn_mfma_f32_32x32x16_bf16(vf[2], p[0], o1, 0, 0, 0); \
;         o0 = __builtin_amdgcn_mfma_f32_32x32x16_bf16(vf[1], p[1], o0, 0, 0, 0); o1 = __builtin_amdgcn_mfma_f32_32x32x16_bf16(vf[3], p[1], o1, 0, 0, 0); } while (0)
; #define A64_SB() __builtin_amdgcn_sched_barrier(0)
; template <int DQK>
; __device__ __forceinline__ void attn_unit64p(LAS char* lds, const bf16x8 (&qa)[DQK / 16], const bf16x8 (&qb)[DQK / 16],
;                                              const bf16_t* Kg, int ldk, const bf16_t* Vg, int ldv, int nt, bf16_t* Obase, int ldo, int ogb_off) {
;     ...
;     A64_SB(); A64_EXP(sb, lb0, lb1, pb); A64_PV(ob0, ob1, pb);
;     __syncthreads();
.Lp11_drain:
	s_setprio 0
	v_exp_f32_e32 v64, v64
	v_exp_f32_e32 v65, v65
	v_exp_f32_e32 v66, v66
	v_exp_f32_e32 v67, v67
	v_exp_f32_e32 v68, v68
	v_exp_f32_e32 v69, v69
	v_cvt_pk_bf16_f32 v230, v64, v65
	v_cvt_pk_bf16_f32 v231, v66, v67
	v_exp_f32_e32 v70, v70
	v_exp_f32_e32 v71, v71
	v_exp_f32_e32 v72, v72
	v_cvt_pk_bf16_f32 v232, v68, v69
	v_exp_f32_e32 v73, v73
	v_exp_f32_e32 v74, v74
	v_cvt_pk_bf16_f32 v233, v70, v71
	v_exp_f32_e32 v75, v75
	v_exp_f32_e32 v76, v76
	v_exp_f32_e32 v77, v77
	v_cvt_pk_bf16_f32 v234, v72, v73
	v_cvt_pk_bf16_f32 v235, v74, v75
	v_exp_f32_e32 v78, v78
	v_exp_f32_e32 v79, v79
	v_cvt_pk_bf16_f32 v236, v76, v77
	v_cvt_pk_bf16_f32 v237, v78, v79
	v_add_f32_e32 v172, v172, v64
	v_add_f32_e32 v173, v173, v65
	v_add_f32_e32 v172, v172, v66
	v_add_f32_e32 v173, v173, v67
	v_add_f32_e32 v172, v172, v68
	v_add_f32_e32 v173, v173, v69
	v_add_f32_e32 v172, v172, v70
	v_add_f32_e32 v173, v173, v71
	v_add_f32_e32 v172, v172, v72
	v_add_f32_e32 v173, v173, v73
	v_add_f32_e32 v172, v172, v74
	v_add_f32_e32 v173, v173, v75
	v_add_f32_e32 v172, v172, v76
	v_add_f32_e32 v173, v173, v77
	v_add_f32_e32 v172, v172, v78
	v_add_f32_e32 v173, v173, v79
	s_nop 1
	v_mfma_f32_32x32x16_bf16 v[16:31], v[248:251], v[230:233], v[16:31]
	v_mfma_f32_32x32x16_bf16 v[0:15], v[252:255], v[230:233], v[0:15]
	v_mfma_f32_32x32x16_bf16 v[16:31], v[214:217], v[234:237], v[16:31]
	v_mfma_f32_32x32x16_bf16 v[0:15], v[218:221], v[234:237], v[0:15]
	s_waitcnt vmcnt(0)
	s_waitcnt lgkmcnt(0)
	s_barrier
	s_branch .LBB0_1115
